# prep phase V^T: per-wave 32-token blocks transposed with ds_read_b64_tr_b16, no workgroup barriers, no 2-byte LDS scatter
# speedup vs baseline: 1.0857x; 1.0072x over previous
.LBB0_384:
	s_or_b64 exec, exec, s[38:39]
	v_readlane_b32 s0, v251, 30
	v_readlane_b32 s1, v251, 31
	s_and_b64 vcc, exec, s[0:1]
	v_and_b32_e32 v14, 7, v59
	s_cbranch_vccz .LBB0_391
	v_readfirstlane_b32 s0, v59
	v_lshrrev_b32_e32 v52, 1, v220
	v_and_b32_e32 v53, 1, v220
	s_lshr_b32 s0, s0, 6
	s_lshl_b32 s1, s68, 3
	s_add_i32 s35, s1, s0
	s_lshl_b32 s36, s28, 3
	s_mul_i32 s1, s0, 0x1200
	s_add_i32 s1, s1, 0x4000
	v_mul_u32_u24_e32 v54, 0x1c00, v52
	v_lshl_add_u32 v54, v53, 6, v54
	v_mul_u32_u24_e32 v56, 0x90, v52
	v_lshl_add_u32 v56, v53, 6, v56
	v_add_u32_e32 v56, s1, v56
	v_and_b32_e32 v15, 15, v220
	v_lshrrev_b32_e32 v60, 4, v220
	v_lshrrev_b32_e32 v40, 2, v15
	v_lshl_add_u32 v40, v60, 3, v40
	v_mul_u32_u24_e32 v40, 0x90, v40
	v_and_b32_e32 v41, 3, v15
	v_lshl_add_u32 v40, v41, 3, v40
	v_add_u32_e32 v40, s1, v40
	v_lshlrev_b32_e32 v41, 6, v15
	v_lshl_add_u32 v41, v60, 4, v41
	v_readlane_b32 s38, v251, 53
	v_readlane_b32 s39, v251, 54
	s_cmp_ge_u32 s35, 0x2200
	s_cbranch_scc1 .Lvt_done
	s_cmp_lt_u32 s35, 0x2000
	s_cbranch_scc0 .Lvt_c_a
	s_lshr_b32 s2, s35, 10
	s_bfe_u32 s3, s35, 0x30007
	s_and_b32 s4, s35, 127
	s_lshl_b32 s5, s2, 12
	s_lshl_b32 s6, s4, 5
	s_add_i32 s5, s5, s6
	s_lshl_b32 s6, s2, 3
	s_add_i32 s6, s6, s3
	s_lshl_b32 s6, s6, 19
	s_lshl_b32 s7, s4, 12
	s_add_i32 s6, s6, s7
	s_branch .Lvt_d_a
.Lvt_c_a:
	s_sub_i32 s2, s35, 0x2000
	s_lshr_b32 s7, s2, 6
	s_bfe_u32 s3, s2, 0x30003
	s_and_b32 s4, s2, 7
	s_lshl_b32 s5, s7, 8
	s_lshl_b32 s6, s4, 5
	s_add_i32 s5, s5, s6
	s_add_i32 s5, s5, 0x8000
	s_lshl_b32 s6, s7, 3
	s_add_i32 s6, s6, s3
	s_lshl_b32 s6, s6, 15
	s_lshl_b32 s7, s4, 12
	s_add_i32 s6, s6, s7
	s_add_i32 s6, s6, 0x2000000
.Lvt_d_a:
	s_mul_i32 s5, s5, 0x1c00
	s_lshl_b32 s3, s3, 7
	s_add_i32 s5, s5, s3
	s_add_i32 s5, s5, 0xc00
	s_add_u32 s40, s70, s5
	s_addc_u32 s41, s71, 0
	s_add_u32 s42, s38, s6
	s_addc_u32 s43, s39, 0
	global_load_dwordx4 v[26:29], v54, s[40:41]
	global_load_dwordx4 v[30:33], v54, s[40:41] offset:16
	global_load_dwordx4 v[44:47], v54, s[40:41] offset:32
	global_load_dwordx4 v[48:51], v54, s[40:41] offset:48
.Lvt_loop:
	s_waitcnt vmcnt(0)
	ds_write_b128 v56, v[26:29]
	ds_write_b128 v56, v[30:33] offset:16
	ds_write_b128 v56, v[44:47] offset:32
	ds_write_b128 v56, v[48:51] offset:48
	s_mov_b32 s44, s42
	s_mov_b32 s45, s43
	s_add_i32 s35, s35, s36
	s_cmp_ge_u32 s35, 0x2200
	s_cbranch_scc1 .Lvt_nonext
	s_cmp_lt_u32 s35, 0x2000
	s_cbranch_scc0 .Lvt_c_b
	s_lshr_b32 s2, s35, 10
	s_bfe_u32 s3, s35, 0x30007
	s_and_b32 s4, s35, 127
	s_lshl_b32 s5, s2, 12
	s_lshl_b32 s6, s4, 5
	s_add_i32 s5, s5, s6
	s_lshl_b32 s6, s2, 3
	s_add_i32 s6, s6, s3
	s_lshl_b32 s6, s6, 19
	s_lshl_b32 s7, s4, 12
	s_add_i32 s6, s6, s7
	s_branch .Lvt_d_b

.Lvt_nonext:
	ds_read_b64_tr_b16 v[0:1], v40
	ds_read_b64_tr_b16 v[2:3], v40 offset:576
	ds_read_b64_tr_b16 v[4:5], v40 offset:32
	ds_read_b64_tr_b16 v[6:7], v40 offset:608
	ds_read_b64_tr_b16 v[10:11], v40 offset:64
	ds_read_b64_tr_b16 v[12:13], v40 offset:640
	ds_read_b64_tr_b16 v[16:17], v40 offset:96
	ds_read_b64_tr_b16 v[18:19], v40 offset:672
	s_waitcnt lgkmcnt(0)
	global_store_dwordx4 v41, v[0:3], s[44:45]
	global_store_dwordx4 v41, v[4:7], s[44:45] offset:1024
	global_store_dwordx4 v41, v[10:13], s[44:45] offset:2048
	global_store_dwordx4 v41, v[16:19], s[44:45] offset:3072
	s_cmp_lt_u32 s35, 0x2200
	s_cbranch_scc1 .Lvt_loop
.Lvt_done:
.LBB0_391:
	s_mov_b32 s0, 0x44000
	v_cmp_gt_i32_e32 vcc, s0, v58
	s_and_saveexec_b64 s[0:1], vcc
	s_cbranch_execz .LBB0_396
	v_readlane_b32 s2, v254, 42
	v_readlane_b32 s36, v253, 48
	v_readlane_b32 s3, v254, 43
	v_add_u32_e32 v0, s2, v14
	v_ashrrev_i32_e32 v1, 31, v0
	v_readlane_b32 s48, v253, 60
	v_readlane_b32 s49, v253, 61
	v_or_b32_e32 v2, s2, v14
	v_readlane_b32 s46, v253, 58
	v_readlane_b32 s47, v253, 59
	v_lshl_add_u64 v[0:1], v[0:1], 2, s[48:49]
	v_ashrrev_i32_e32 v3, 31, v2
	v_readlane_b32 s2, v251, 14
	v_cmp_gt_u32_e32 vcc, 4, v14
	v_lshl_add_u64 v[0:1], v[0:1], 0, -16
	v_lshl_add_u64 v[2:3], v[2:3], 2, s[46:47]
	v_ashrrev_i32_e32 v59, 31, v58
	v_readlane_b32 s3, v251, 15
	s_ashr_i32 s35, s34, 31
	v_cndmask_b32_e32 v1, v1, v3, vcc
	v_cndmask_b32_e32 v0, v0, v2, vcc
	v_lshl_add_u64 v[2:3], v[58:59], 2, s[2:3]
	s_lshl_b64 s[4:5], s[34:35], 2
	s_mov_b64 s[6:7], 0
	v_readlane_b32 s37, v253, 49
	v_readlane_b32 s38, v253, 50
	v_readlane_b32 s39, v253, 51
	v_readlane_b32 s40, v253, 52
	v_readlane_b32 s41, v253, 53
	v_readlane_b32 s42, v253, 54
	v_readlane_b32 s43, v253, 55
	v_readlane_b32 s44, v253, 56
	v_readlane_b32 s45, v253, 57
	v_readlane_b32 s50, v253, 62
	v_readlane_b32 s51, v253, 63
	s_branch .LBB0_394
